# P4 out-proj epilogue rewritten: 32 residual loads batched 16 in flight instead of load+vmcnt(0) each
# baseline (speedup 1.0000x reference)
.LBB0_430:
	v_lshl_add_u32 v151, s22, 8, v144
	v_lshl_or_b32 v152, s24, 8, v146
	v_lshl_add_u32 v153, v151, 10, v152
	v_lshlrev_b32_e32 v154, 2, v153
	s_add_u32 s74, s72, 0x0
	s_addc_u32 s75, s73, 0
	global_load_dwordx4 v[188:191], v154, s[74:75]
	global_load_dwordx4 v[192:195], v154, s[74:75] offset:64
	global_load_dwordx4 v[196:199], v154, s[74:75] offset:512
	global_load_dwordx4 v[200:203], v154, s[74:75] offset:576
	s_add_u32 s74, s72, 0x10000
	s_addc_u32 s75, s73, 0
	global_load_dwordx4 v[204:207], v154, s[74:75]
	global_load_dwordx4 v[208:211], v154, s[74:75] offset:64
	global_load_dwordx4 v[212:215], v154, s[74:75] offset:512
	global_load_dwordx4 v[216:219], v154, s[74:75] offset:576
	s_add_u32 s74, s72, 0x20000
	s_addc_u32 s75, s73, 0
	global_load_dwordx4 v[220:223], v154, s[74:75]
	global_load_dwordx4 v[224:227], v154, s[74:75] offset:64
	global_load_dwordx4 v[228:231], v154, s[74:75] offset:512
	global_load_dwordx4 v[232:235], v154, s[74:75] offset:576
	s_add_u32 s74, s72, 0x30000
	s_addc_u32 s75, s73, 0
	global_load_dwordx4 v[236:239], v154, s[74:75]
	global_load_dwordx4 v[240:243], v154, s[74:75] offset:64
	global_load_dwordx4 v[244:247], v154, s[74:75] offset:512
	global_load_dwordx4 v[248:251], v154, s[74:75] offset:576
	v_lshlrev_b32_e32 v155, 1, v153
	v_lshlrev_b32_e32 v156, 3, v151
	v_xor_b32_e32 v157, 16, v150
	v_lshlrev_b32_e32 v157, 2, v157
	v_xor_b32_e32 v158, 32, v150
	v_lshlrev_b32_e32 v158, 2, v158
	s_waitcnt vmcnt(12)
	v_pk_fma_f32 v[188:189], v[188:189], s[12:13], v[124:125] op_sel_hi:[1,0,1]
	v_pk_fma_f32 v[190:191], v[190:191], s[12:13], v[126:127] op_sel_hi:[1,0,1]
	v_pk_fma_f32 v[192:193], v[192:193], s[12:13], v[120:121] op_sel_hi:[1,0,1]
	v_pk_fma_f32 v[194:195], v[194:195], s[12:13], v[122:123] op_sel_hi:[1,0,1]
	v_pk_fma_f32 v[196:197], v[196:197], s[12:13], v[116:117] op_sel_hi:[1,0,1]
	v_pk_fma_f32 v[198:199], v[198:199], s[12:13], v[118:119] op_sel_hi:[1,0,1]
	v_pk_fma_f32 v[200:201], v[200:201], s[12:13], v[112:113] op_sel_hi:[1,0,1]
	v_pk_fma_f32 v[202:203], v[202:203], s[12:13], v[114:115] op_sel_hi:[1,0,1]
	s_add_u32 s82, s88, 0x0
	s_addc_u32 s83, s89, 0
	v_cvt_pk_bf16_f32 v160, v188, v189
	v_cvt_pk_bf16_f32 v161, v190, v191
	global_store_dwordx2 v155, v[160:161], s[82:83]
	v_cvt_pk_bf16_f32 v162, v192, v193
	v_cvt_pk_bf16_f32 v163, v194, v195
	global_store_dwordx2 v155, v[162:163], s[82:83] offset:32
	v_cvt_pk_bf16_f32 v164, v196, v197
	v_cvt_pk_bf16_f32 v165, v198, v199
	global_store_dwordx2 v155, v[164:165], s[82:83] offset:256
	v_cvt_pk_bf16_f32 v166, v200, v201
	v_cvt_pk_bf16_f32 v167, v202, v203
	global_store_dwordx2 v155, v[166:167], s[82:83] offset:288
	v_add_f32_e32 v168, v188, v189
	v_add_f32_e32 v169, v190, v191
	v_mul_f32_e32 v172, v189, v189
	v_mul_f32_e32 v173, v191, v191
	v_add_f32_e32 v168, v168, v169
	v_fma_f32 v172, v188, v188, v172
	v_fma_f32 v173, v190, v190, v173
	v_add_f32_e32 v170, 0, v168
	v_add_f32_e32 v171, v172, v173
	v_add_f32_e32 v168, v192, v193
	v_add_f32_e32 v169, v194, v195
	v_mul_f32_e32 v172, v193, v193
	v_mul_f32_e32 v173, v195, v195
	v_add_f32_e32 v168, v168, v169
	v_fma_f32 v172, v192, v192, v172
	v_fma_f32 v173, v194, v194, v173
	v_add_f32_e32 v170, v170, v168
	v_add_f32_e32 v172, v172, v173
	v_add_f32_e32 v171, v171, v172
	v_add_f32_e32 v168, v196, v197
	v_add_f32_e32 v169, v198, v199
	v_mul_f32_e32 v172, v197, v197
	v_mul_f32_e32 v173, v199, v199
	v_add_f32_e32 v168, v168, v169
	v_fma_f32 v172, v196, v196, v172
	v_fma_f32 v173, v198, v198, v173
	v_add_f32_e32 v170, v170, v168
	v_add_f32_e32 v172, v172, v173
	v_add_f32_e32 v171, v171, v172
	v_add_f32_e32 v168, v200, v201
	v_add_f32_e32 v169, v202, v203
	v_mul_f32_e32 v172, v201, v201
	v_mul_f32_e32 v173, v203, v203
	v_add_f32_e32 v168, v168, v169
	v_fma_f32 v172, v200, v200, v172
	v_fma_f32 v173, v202, v202, v173
	v_add_f32_e32 v170, v170, v168
	v_add_f32_e32 v172, v172, v173
	v_add_f32_e32 v171, v171, v172
	s_add_u32 s74, s72, 0x80000
	s_addc_u32 s75, s73, 0
	global_load_dwordx4 v[188:191], v154, s[74:75]
	global_load_dwordx4 v[192:195], v154, s[74:75] offset:64
	global_load_dwordx4 v[196:199], v154, s[74:75] offset:512
	global_load_dwordx4 v[200:203], v154, s[74:75] offset:576
	ds_bpermute_b32 v174, v157, v170
	ds_bpermute_b32 v175, v157, v171
	s_waitcnt lgkmcnt(0)
	v_add_f32_e32 v170, v170, v174
	v_add_f32_e32 v171, v171, v175
	ds_bpermute_b32 v174, v158, v170
	ds_bpermute_b32 v175, v158, v171
	s_waitcnt lgkmcnt(0)
	v_add_f32_e32 v170, v170, v174
	v_add_f32_e32 v171, v171, v175
	s_and_saveexec_b64 s[22:23], s[2:3]
	global_atomic_add_f32 v156, v170, s[6:7]
	global_atomic_add_f32 v156, v171, s[6:7] offset:4
	s_or_b64 exec, exec, s[22:23]
	s_waitcnt vmcnt(18)
	v_pk_fma_f32 v[204:205], v[204:205], s[12:13], v[108:109] op_sel_hi:[1,0,1]
	v_pk_fma_f32 v[206:207], v[206:207], s[12:13], v[110:111] op_sel_hi:[1,0,1]
	v_pk_fma_f32 v[208:209], v[208:209], s[12:13], v[104:105] op_sel_hi:[1,0,1]
	v_pk_fma_f32 v[210:211], v[210:211], s[12:13], v[106:107] op_sel_hi:[1,0,1]
	v_pk_fma_f32 v[212:213], v[212:213], s[12:13], v[100:101] op_sel_hi:[1,0,1]
	v_pk_fma_f32 v[214:215], v[214:215], s[12:13], v[102:103] op_sel_hi:[1,0,1]
	v_pk_fma_f32 v[216:217], v[216:217], s[12:13], v[96:97] op_sel_hi:[1,0,1]
	v_pk_fma_f32 v[218:219], v[218:219], s[12:13], v[98:99] op_sel_hi:[1,0,1]
	s_add_u32 s82, s88, 0x8000
	s_addc_u32 s83, s89, 0
	v_cvt_pk_bf16_f32 v160, v204, v205
	v_cvt_pk_bf16_f32 v161, v206, v207
	global_store_dwordx2 v155, v[160:161], s[82:83]
	v_cvt_pk_bf16_f32 v162, v208, v209
	v_cvt_pk_bf16_f32 v163, v210, v211
	global_store_dwordx2 v155, v[162:163], s[82:83] offset:32
	v_cvt_pk_bf16_f32 v164, v212, v213
	v_cvt_pk_bf16_f32 v165, v214, v215
	global_store_dwordx2 v155, v[164:165], s[82:83] offset:256
	v_cvt_pk_bf16_f32 v166, v216, v217
	v_cvt_pk_bf16_f32 v167, v218, v219
	global_store_dwordx2 v155, v[166:167], s[82:83] offset:288
	v_add_f32_e32 v168, v204, v205
	v_add_f32_e32 v169, v206, v207
	v_mul_f32_e32 v172, v205, v205
	v_mul_f32_e32 v173, v207, v207
	v_add_f32_e32 v168, v168, v169
	v_fma_f32 v172, v204, v204, v172
	v_fma_f32 v173, v206, v206, v173
	v_add_f32_e32 v170, 0, v168
	v_add_f32_e32 v171, v172, v173
	v_add_f32_e32 v168, v208, v209
	v_add_f32_e32 v169, v210, v211
	v_mul_f32_e32 v172, v209, v209
	v_mul_f32_e32 v173, v211, v211
	v_add_f32_e32 v168, v168, v169
	v_fma_f32 v172, v208, v208, v172
	v_fma_f32 v173, v210, v210, v173
	v_add_f32_e32 v170, v170, v168
	v_add_f32_e32 v172, v172, v173
	v_add_f32_e32 v171, v171, v172
	v_add_f32_e32 v168, v212, v213
	v_add_f32_e32 v169, v214, v215
	v_mul_f32_e32 v172, v213, v213
	v_mul_f32_e32 v173, v215, v215
	v_add_f32_e32 v168, v168, v169
	v_fma_f32 v172, v212, v212, v172
	v_fma_f32 v173, v214, v214, v173
	v_add_f32_e32 v170, v170, v168
	v_add_f32_e32 v172, v172, v173
	v_add_f32_e32 v171, v171, v172
	v_add_f32_e32 v168, v216, v217
	v_add_f32_e32 v169, v218, v219
	v_mul_f32_e32 v172, v217, v217
	v_mul_f32_e32 v173, v219, v219
	v_add_f32_e32 v168, v168, v169
	v_fma_f32 v172, v216, v216, v172
	v_fma_f32 v173, v218, v218, v173
	v_add_f32_e32 v170, v170, v168
	v_add_f32_e32 v172, v172, v173
	v_add_f32_e32 v171, v171, v172
	s_add_u32 s74, s72, 0x90000
	s_addc_u32 s75, s73, 0
	global_load_dwordx4 v[204:207], v154, s[74:75]
	global_load_dwordx4 v[208:211], v154, s[74:75] offset:64
	global_load_dwordx4 v[212:215], v154, s[74:75] offset:512
	global_load_dwordx4 v[216:219], v154, s[74:75] offset:576
	ds_bpermute_b32 v174, v157, v170
	ds_bpermute_b32 v175, v157, v171
	s_waitcnt lgkmcnt(0)
	v_add_f32_e32 v170, v170, v174
	v_add_f32_e32 v171, v171, v175
	ds_bpermute_b32 v174, v158, v170
	ds_bpermute_b32 v175, v158, v171
	s_waitcnt lgkmcnt(0)
	v_add_f32_e32 v170, v170, v174
	v_add_f32_e32 v171, v171, v175
	s_and_saveexec_b64 s[22:23], s[2:3]
	global_atomic_add_f32 v156, v170, s[6:7] offset:128
	global_atomic_add_f32 v156, v171, s[6:7] offset:132
	s_or_b64 exec, exec, s[22:23]
	s_waitcnt vmcnt(24)
	v_pk_fma_f32 v[220:221], v[220:221], s[12:13], v[92:93] op_sel_hi:[1,0,1]
	v_pk_fma_f32 v[222:223], v[222:223], s[12:13], v[94:95] op_sel_hi:[1,0,1]
	v_pk_fma_f32 v[224:225], v[224:225], s[12:13], v[88:89] op_sel_hi:[1,0,1]
	v_pk_fma_f32 v[226:227], v[226:227], s[12:13], v[90:91] op_sel_hi:[1,0,1]
	v_pk_fma_f32 v[228:229], v[228:229], s[12:13], v[84:85] op_sel_hi:[1,0,1]
	v_pk_fma_f32 v[230:231], v[230:231], s[12:13], v[86:87] op_sel_hi:[1,0,1]
	v_pk_fma_f32 v[232:233], v[232:233], s[12:13], v[80:81] op_sel_hi:[1,0,1]
	v_pk_fma_f32 v[234:235], v[234:235], s[12:13], v[82:83] op_sel_hi:[1,0,1]
	s_add_u32 s82, s88, 0x10000
	s_addc_u32 s83, s89, 0
	v_cvt_pk_bf16_f32 v160, v220, v221
	v_cvt_pk_bf16_f32 v161, v222, v223
	global_store_dwordx2 v155, v[160:161], s[82:83]
	v_cvt_pk_bf16_f32 v162, v224, v225
	v_cvt_pk_bf16_f32 v163, v226, v227
	global_store_dwordx2 v155, v[162:163], s[82:83] offset:32
	v_cvt_pk_bf16_f32 v164, v228, v229
	v_cvt_pk_bf16_f32 v165, v230, v231
	global_store_dwordx2 v155, v[164:165], s[82:83] offset:256
	v_cvt_pk_bf16_f32 v166, v232, v233
	v_cvt_pk_bf16_f32 v167, v234, v235
	global_store_dwordx2 v155, v[166:167], s[82:83] offset:288
	v_add_f32_e32 v168, v220, v221
	v_add_f32_e32 v169, v222, v223
	v_mul_f32_e32 v172, v221, v221
	v_mul_f32_e32 v173, v223, v223
	v_add_f32_e32 v168, v168, v169
	v_fma_f32 v172, v220, v220, v172
	v_fma_f32 v173, v222, v222, v173
	v_add_f32_e32 v170, 0, v168
	v_add_f32_e32 v171, v172, v173
	v_add_f32_e32 v168, v224, v225
	v_add_f32_e32 v169, v226, v227
	v_mul_f32_e32 v172, v225, v225
	v_mul_f32_e32 v173, v227, v227
	v_add_f32_e32 v168, v168, v169
	v_fma_f32 v172, v224, v224, v172
	v_fma_f32 v173, v226, v226, v173
	v_add_f32_e32 v170, v170, v168
	v_add_f32_e32 v172, v172, v173
	v_add_f32_e32 v171, v171, v172
	v_add_f32_e32 v168, v228, v229
	v_add_f32_e32 v169, v230, v231
	v_mul_f32_e32 v172, v229, v229
	v_mul_f32_e32 v173, v231, v231
	v_add_f32_e32 v168, v168, v169
	v_fma_f32 v172, v228, v228, v172
	v_fma_f32 v173, v230, v230, v173
	v_add_f32_e32 v170, v170, v168
	v_add_f32_e32 v172, v172, v173
	v_add_f32_e32 v171, v171, v172
	v_add_f32_e32 v168, v232, v233
	v_add_f32_e32 v169, v234, v235
	v_mul_f32_e32 v172, v233, v233
	v_mul_f32_e32 v173, v235, v235
	v_add_f32_e32 v168, v168, v169
	v_fma_f32 v172, v232, v232, v172
	v_fma_f32 v173, v234, v234, v173
	v_add_f32_e32 v170, v170, v168
	v_add_f32_e32 v172, v172, v173
	v_add_f32_e32 v171, v171, v172
	s_add_u32 s74, s72, 0xa0000
	s_addc_u32 s75, s73, 0
	global_load_dwordx4 v[220:223], v154, s[74:75]
	global_load_dwordx4 v[224:227], v154, s[74:75] offset:64
	global_load_dwordx4 v[228:231], v154, s[74:75] offset:512
	global_load_dwordx4 v[232:235], v154, s[74:75] offset:576
	ds_bpermute_b32 v174, v157, v170
	ds_bpermute_b32 v175, v157, v171
	s_waitcnt lgkmcnt(0)
	v_add_f32_e32 v170, v170, v174
	v_add_f32_e32 v171, v171, v175
	ds_bpermute_b32 v174, v158, v170
	ds_bpermute_b32 v175, v158, v171
	s_waitcnt lgkmcnt(0)
	v_add_f32_e32 v170, v170, v174
	v_add_f32_e32 v171, v171, v175
	s_and_saveexec_b64 s[22:23], s[2:3]
	global_atomic_add_f32 v156, v170, s[6:7] offset:256
	global_atomic_add_f32 v156, v171, s[6:7] offset:260
	s_or_b64 exec, exec, s[22:23]
	s_waitcnt vmcnt(30)
	v_pk_fma_f32 v[236:237], v[236:237], s[12:13], v[76:77] op_sel_hi:[1,0,1]
	v_pk_fma_f32 v[238:239], v[238:239], s[12:13], v[78:79] op_sel_hi:[1,0,1]
	v_pk_fma_f32 v[240:241], v[240:241], s[12:13], v[72:73] op_sel_hi:[1,0,1]
	v_pk_fma_f32 v[242:243], v[242:243], s[12:13], v[74:75] op_sel_hi:[1,0,1]
	v_pk_fma_f32 v[244:245], v[244:245], s[12:13], v[68:69] op_sel_hi:[1,0,1]
	v_pk_fma_f32 v[246:247], v[246:247], s[12:13], v[70:71] op_sel_hi:[1,0,1]
	v_pk_fma_f32 v[248:249], v[248:249], s[12:13], v[64:65] op_sel_hi:[1,0,1]
	v_pk_fma_f32 v[250:251], v[250:251], s[12:13], v[66:67] op_sel_hi:[1,0,1]
	s_add_u32 s82, s88, 0x18000
	s_addc_u32 s83, s89, 0
	v_cvt_pk_bf16_f32 v160, v236, v237
	v_cvt_pk_bf16_f32 v161, v238, v239
	global_store_dwordx2 v155, v[160:161], s[82:83]
	v_cvt_pk_bf16_f32 v162, v240, v241
	v_cvt_pk_bf16_f32 v163, v242, v243
	global_store_dwordx2 v155, v[162:163], s[82:83] offset:32
	v_cvt_pk_bf16_f32 v164, v244, v245
	v_cvt_pk_bf16_f32 v165, v246, v247
	global_store_dwordx2 v155, v[164:165], s[82:83] offset:256
	v_cvt_pk_bf16_f32 v166, v248, v249
	v_cvt_pk_bf16_f32 v167, v250, v251
	global_store_dwordx2 v155, v[166:167], s[82:83] offset:288
	v_add_f32_e32 v168, v236, v237
	v_add_f32_e32 v169, v238, v239
	v_mul_f32_e32 v172, v237, v237
	v_mul_f32_e32 v173, v239, v239
	v_add_f32_e32 v168, v168, v169
	v_fma_f32 v172, v236, v236, v172
	v_fma_f32 v173, v238, v238, v173
	v_add_f32_e32 v170, 0, v168
	v_add_f32_e32 v171, v172, v173
	v_add_f32_e32 v168, v240, v241
	v_add_f32_e32 v169, v242, v243
	v_mul_f32_e32 v172, v241, v241
	v_mul_f32_e32 v173, v243, v243
	v_add_f32_e32 v168, v168, v169
	v_fma_f32 v172, v240, v240, v172
	v_fma_f32 v173, v242, v242, v173
	v_add_f32_e32 v170, v170, v168
	v_add_f32_e32 v172, v172, v173
	v_add_f32_e32 v171, v171, v172
	v_add_f32_e32 v168, v244, v245
	v_add_f32_e32 v169, v246, v247
	v_mul_f32_e32 v172, v245, v245
	v_mul_f32_e32 v173, v247, v247
	v_add_f32_e32 v168, v168, v169
	v_fma_f32 v172, v244, v244, v172
	v_fma_f32 v173, v246, v246, v173
	v_add_f32_e32 v170, v170, v168
	v_add_f32_e32 v172, v172, v173
	v_add_f32_e32 v171, v171, v172
	v_add_f32_e32 v168, v248, v249
	v_add_f32_e32 v169, v250, v251
	v_mul_f32_e32 v172, v249, v249
	v_mul_f32_e32 v173, v251, v251
	v_add_f32_e32 v168, v168, v169
	v_fma_f32 v172, v248, v248, v172
	v_fma_f32 v173, v250, v250, v173
	v_add_f32_e32 v170, v170, v168
	v_add_f32_e32 v172, v172, v173
	v_add_f32_e32 v171, v171, v172
	s_add_u32 s74, s72, 0xb0000
	s_addc_u32 s75, s73, 0
	global_load_dwordx4 v[236:239], v154, s[74:75]
	global_load_dwordx4 v[240:243], v154, s[74:75] offset:64
	global_load_dwordx4 v[244:247], v154, s[74:75] offset:512
	global_load_dwordx4 v[248:251], v154, s[74:75] offset:576
	ds_bpermute_b32 v174, v157, v170
	ds_bpermute_b32 v175, v157, v171
	s_waitcnt lgkmcnt(0)
	v_add_f32_e32 v170, v170, v174
	v_add_f32_e32 v171, v171, v175
	ds_bpermute_b32 v174, v158, v170
	ds_bpermute_b32 v175, v158, v171
	s_waitcnt lgkmcnt(0)
	v_add_f32_e32 v170, v170, v174
	v_add_f32_e32 v171, v171, v175
	s_and_saveexec_b64 s[22:23], s[2:3]
	global_atomic_add_f32 v156, v170, s[6:7] offset:384
	global_atomic_add_f32 v156, v171, s[6:7] offset:388
	s_or_b64 exec, exec, s[22:23]
	s_waitcnt vmcnt(32)
	v_pk_fma_f32 v[188:189], v[188:189], s[12:13], v[60:61] op_sel_hi:[1,0,1]
	v_pk_fma_f32 v[190:191], v[190:191], s[12:13], v[62:63] op_sel_hi:[1,0,1]
	v_pk_fma_f32 v[192:193], v[192:193], s[12:13], v[56:57] op_sel_hi:[1,0,1]
	v_pk_fma_f32 v[194:195], v[194:195], s[12:13], v[58:59] op_sel_hi:[1,0,1]
	v_pk_fma_f32 v[196:197], v[196:197], s[12:13], v[52:53] op_sel_hi:[1,0,1]
	v_pk_fma_f32 v[198:199], v[198:199], s[12:13], v[54:55] op_sel_hi:[1,0,1]
	v_pk_fma_f32 v[200:201], v[200:201], s[12:13], v[48:49] op_sel_hi:[1,0,1]
	v_pk_fma_f32 v[202:203], v[202:203], s[12:13], v[50:51] op_sel_hi:[1,0,1]
	s_add_u32 s82, s88, 0x40000
	s_addc_u32 s83, s89, 0
	v_cvt_pk_bf16_f32 v160, v188, v189
	v_cvt_pk_bf16_f32 v161, v190, v191
	global_store_dwordx2 v155, v[160:161], s[82:83]
	v_cvt_pk_bf16_f32 v162, v192, v193
	v_cvt_pk_bf16_f32 v163, v194, v195
	global_store_dwordx2 v155, v[162:163], s[82:83] offset:32
	v_cvt_pk_bf16_f32 v164, v196, v197
	v_cvt_pk_bf16_f32 v165, v198, v199
	global_store_dwordx2 v155, v[164:165], s[82:83] offset:256
	v_cvt_pk_bf16_f32 v166, v200, v201
	v_cvt_pk_bf16_f32 v167, v202, v203
	global_store_dwordx2 v155, v[166:167], s[82:83] offset:288
	v_add_f32_e32 v168, v188, v189
	v_add_f32_e32 v169, v190, v191
	v_mul_f32_e32 v172, v189, v189
	v_mul_f32_e32 v173, v191, v191
	v_add_f32_e32 v168, v168, v169
	v_fma_f32 v172, v188, v188, v172
	v_fma_f32 v173, v190, v190, v173
	v_add_f32_e32 v170, 0, v168
	v_add_f32_e32 v171, v172, v173
	v_add_f32_e32 v168, v192, v193
	v_add_f32_e32 v169, v194, v195
	v_mul_f32_e32 v172, v193, v193
	v_mul_f32_e32 v173, v195, v195
	v_add_f32_e32 v168, v168, v169
	v_fma_f32 v172, v192, v192, v172
	v_fma_f32 v173, v194, v194, v173
	v_add_f32_e32 v170, v170, v168
	v_add_f32_e32 v172, v172, v173
	v_add_f32_e32 v171, v171, v172
	v_add_f32_e32 v168, v196, v197
	v_add_f32_e32 v169, v198, v199
	v_mul_f32_e32 v172, v197, v197
	v_mul_f32_e32 v173, v199, v199
	v_add_f32_e32 v168, v168, v169
	v_fma_f32 v172, v196, v196, v172
	v_fma_f32 v173, v198, v198, v173
	v_add_f32_e32 v170, v170, v168
	v_add_f32_e32 v172, v172, v173
	v_add_f32_e32 v171, v171, v172
	v_add_f32_e32 v168, v200, v201
	v_add_f32_e32 v169, v202, v203
	v_mul_f32_e32 v172, v201, v201
	v_mul_f32_e32 v173, v203, v203
	v_add_f32_e32 v168, v168, v169
	v_fma_f32 v172, v200, v200, v172
	v_fma_f32 v173, v202, v202, v173
	v_add_f32_e32 v170, v170, v168
	v_add_f32_e32 v172, v172, v173
	v_add_f32_e32 v171, v171, v172
	ds_bpermute_b32 v174, v157, v170
	ds_bpermute_b32 v175, v157, v171
	s_waitcnt lgkmcnt(0)
	v_add_f32_e32 v170, v170, v174
	v_add_f32_e32 v171, v171, v175
	ds_bpermute_b32 v174, v158, v170
	ds_bpermute_b32 v175, v158, v171
	s_waitcnt lgkmcnt(0)
	v_add_f32_e32 v170, v170, v174
	v_add_f32_e32 v171, v171, v175
	s_and_saveexec_b64 s[22:23], s[2:3]
	global_atomic_add_f32 v156, v170, s[6:7] offset:1024
	global_atomic_add_f32 v156, v171, s[6:7] offset:1028
	s_or_b64 exec, exec, s[22:23]
	s_waitcnt vmcnt(28)
	v_pk_fma_f32 v[204:205], v[204:205], s[12:13], v[44:45] op_sel_hi:[1,0,1]
	v_pk_fma_f32 v[206:207], v[206:207], s[12:13], v[46:47] op_sel_hi:[1,0,1]
	v_pk_fma_f32 v[208:209], v[208:209], s[12:13], v[40:41] op_sel_hi:[1,0,1]
	v_pk_fma_f32 v[210:211], v[210:211], s[12:13], v[42:43] op_sel_hi:[1,0,1]
	v_pk_fma_f32 v[212:213], v[212:213], s[12:13], v[36:37] op_sel_hi:[1,0,1]
	v_pk_fma_f32 v[214:215], v[214:215], s[12:13], v[38:39] op_sel_hi:[1,0,1]
	v_pk_fma_f32 v[216:217], v[216:217], s[12:13], v[32:33] op_sel_hi:[1,0,1]
	v_pk_fma_f32 v[218:219], v[218:219], s[12:13], v[34:35] op_sel_hi:[1,0,1]
	s_add_u32 s82, s88, 0x48000
	s_addc_u32 s83, s89, 0
	v_cvt_pk_bf16_f32 v160, v204, v205
	v_cvt_pk_bf16_f32 v161, v206, v207
	global_store_dwordx2 v155, v[160:161], s[82:83]
	v_cvt_pk_bf16_f32 v162, v208, v209
	v_cvt_pk_bf16_f32 v163, v210, v211
	global_store_dwordx2 v155, v[162:163], s[82:83] offset:32
	v_cvt_pk_bf16_f32 v164, v212, v213
	v_cvt_pk_bf16_f32 v165, v214, v215
	global_store_dwordx2 v155, v[164:165], s[82:83] offset:256
	v_cvt_pk_bf16_f32 v166, v216, v217
	v_cvt_pk_bf16_f32 v167, v218, v219
	global_store_dwordx2 v155, v[166:167], s[82:83] offset:288
	v_add_f32_e32 v168, v204, v205
	v_add_f32_e32 v169, v206, v207
	v_mul_f32_e32 v172, v205, v205
	v_mul_f32_e32 v173, v207, v207
	v_add_f32_e32 v168, v168, v169
	v_fma_f32 v172, v204, v204, v172
	v_fma_f32 v173, v206, v206, v173
	v_add_f32_e32 v170, 0, v168
	v_add_f32_e32 v171, v172, v173
	v_add_f32_e32 v168, v208, v209
	v_add_f32_e32 v169, v210, v211
	v_mul_f32_e32 v172, v209, v209
	v_mul_f32_e32 v173, v211, v211
	v_add_f32_e32 v168, v168, v169
	v_fma_f32 v172, v208, v208, v172
	v_fma_f32 v173, v210, v210, v173
	v_add_f32_e32 v170, v170, v168
	v_add_f32_e32 v172, v172, v173
	v_add_f32_e32 v171, v171, v172
	v_add_f32_e32 v168, v212, v213
	v_add_f32_e32 v169, v214, v215
	v_mul_f32_e32 v172, v213, v213
	v_mul_f32_e32 v173, v215, v215
	v_add_f32_e32 v168, v168, v169
	v_fma_f32 v172, v212, v212, v172
	v_fma_f32 v173, v214, v214, v173
	v_add_f32_e32 v170, v170, v168
	v_add_f32_e32 v172, v172, v173
	v_add_f32_e32 v171, v171, v172
	v_add_f32_e32 v168, v216, v217
	v_add_f32_e32 v169, v218, v219
	v_mul_f32_e32 v172, v217, v217
	v_mul_f32_e32 v173, v219, v219
	v_add_f32_e32 v168, v168, v169
	v_fma_f32 v172, v216, v216, v172
	v_fma_f32 v173, v218, v218, v173
	v_add_f32_e32 v170, v170, v168
	v_add_f32_e32 v172, v172, v173
	v_add_f32_e32 v171, v171, v172
	ds_bpermute_b32 v174, v157, v170
	ds_bpermute_b32 v175, v157, v171
	s_waitcnt lgkmcnt(0)
	v_add_f32_e32 v170, v170, v174
	v_add_f32_e32 v171, v171, v175
	ds_bpermute_b32 v174, v158, v170
	ds_bpermute_b32 v175, v158, v171
	s_waitcnt lgkmcnt(0)
	v_add_f32_e32 v170, v170, v174
	v_add_f32_e32 v171, v171, v175
	s_and_saveexec_b64 s[22:23], s[2:3]
	global_atomic_add_f32 v156, v170, s[6:7] offset:1152
	global_atomic_add_f32 v156, v171, s[6:7] offset:1156
	s_or_b64 exec, exec, s[22:23]
	s_waitcnt vmcnt(24)
	v_pk_fma_f32 v[220:221], v[220:221], s[12:13], v[28:29] op_sel_hi:[1,0,1]
	v_pk_fma_f32 v[222:223], v[222:223], s[12:13], v[30:31] op_sel_hi:[1,0,1]
	v_pk_fma_f32 v[224:225], v[224:225], s[12:13], v[24:25] op_sel_hi:[1,0,1]
	v_pk_fma_f32 v[226:227], v[226:227], s[12:13], v[26:27] op_sel_hi:[1,0,1]
	v_pk_fma_f32 v[228:229], v[228:229], s[12:13], v[20:21] op_sel_hi:[1,0,1]
	v_pk_fma_f32 v[230:231], v[230:231], s[12:13], v[22:23] op_sel_hi:[1,0,1]
	v_pk_fma_f32 v[232:233], v[232:233], s[12:13], v[16:17] op_sel_hi:[1,0,1]
	v_pk_fma_f32 v[234:235], v[234:235], s[12:13], v[18:19] op_sel_hi:[1,0,1]
	s_add_u32 s82, s88, 0x50000
	s_addc_u32 s83, s89, 0
	v_cvt_pk_bf16_f32 v160, v220, v221
	v_cvt_pk_bf16_f32 v161, v222, v223
	global_store_dwordx2 v155, v[160:161], s[82:83]
	v_cvt_pk_bf16_f32 v162, v224, v225
	v_cvt_pk_bf16_f32 v163, v226, v227
	global_store_dwordx2 v155, v[162:163], s[82:83] offset:32
	v_cvt_pk_bf16_f32 v164, v228, v229
	v_cvt_pk_bf16_f32 v165, v230, v231
	global_store_dwordx2 v155, v[164:165], s[82:83] offset:256
	v_cvt_pk_bf16_f32 v166, v232, v233
	v_cvt_pk_bf16_f32 v167, v234, v235
	global_store_dwordx2 v155, v[166:167], s[82:83] offset:288
	v_add_f32_e32 v168, v220, v221
	v_add_f32_e32 v169, v222, v223
	v_mul_f32_e32 v172, v221, v221
	v_mul_f32_e32 v173, v223, v223
	v_add_f32_e32 v168, v168, v169
	v_fma_f32 v172, v220, v220, v172
	v_fma_f32 v173, v222, v222, v173
	v_add_f32_e32 v170, 0, v168
	v_add_f32_e32 v171, v172, v173
	v_add_f32_e32 v168, v224, v225
	v_add_f32_e32 v169, v226, v227
	v_mul_f32_e32 v172, v225, v225
	v_mul_f32_e32 v173, v227, v227
	v_add_f32_e32 v168, v168, v169
	v_fma_f32 v172, v224, v224, v172
	v_fma_f32 v173, v226, v226, v173
	v_add_f32_e32 v170, v170, v168
	v_add_f32_e32 v172, v172, v173
	v_add_f32_e32 v171, v171, v172
	v_add_f32_e32 v168, v228, v229
	v_add_f32_e32 v169, v230, v231
	v_mul_f32_e32 v172, v229, v229
	v_mul_f32_e32 v173, v231, v231
	v_add_f32_e32 v168, v168, v169
	v_fma_f32 v172, v228, v228, v172
	v_fma_f32 v173, v230, v230, v173
	v_add_f32_e32 v170, v170, v168
	v_add_f32_e32 v172, v172, v173
	v_add_f32_e32 v171, v171, v172
	v_add_f32_e32 v168, v232, v233
	v_add_f32_e32 v169, v234, v235
	v_mul_f32_e32 v172, v233, v233
	v_mul_f32_e32 v173, v235, v235
	v_add_f32_e32 v168, v168, v169
	v_fma_f32 v172, v232, v232, v172
	v_fma_f32 v173, v234, v234, v173
	v_add_f32_e32 v170, v170, v168
	v_add_f32_e32 v172, v172, v173
	v_add_f32_e32 v171, v171, v172
	ds_bpermute_b32 v174, v157, v170
	ds_bpermute_b32 v175, v157, v171
	s_waitcnt lgkmcnt(0)
	v_add_f32_e32 v170, v170, v174
	v_add_f32_e32 v171, v171, v175
	ds_bpermute_b32 v174, v158, v170
	ds_bpermute_b32 v175, v158, v171
	s_waitcnt lgkmcnt(0)
	v_add_f32_e32 v170, v170, v174
	v_add_f32_e32 v171, v171, v175
	s_and_saveexec_b64 s[22:23], s[2:3]
	global_atomic_add_f32 v156, v170, s[6:7] offset:1280
	global_atomic_add_f32 v156, v171, s[6:7] offset:1284
	s_or_b64 exec, exec, s[22:23]
	s_waitcnt vmcnt(20)
	v_pk_fma_f32 v[236:237], v[236:237], s[12:13], v[12:13] op_sel_hi:[1,0,1]
	v_pk_fma_f32 v[238:239], v[238:239], s[12:13], v[14:15] op_sel_hi:[1,0,1]
	v_pk_fma_f32 v[240:241], v[240:241], s[12:13], v[8:9] op_sel_hi:[1,0,1]
	v_pk_fma_f32 v[242:243], v[242:243], s[12:13], v[10:11] op_sel_hi:[1,0,1]
	v_pk_fma_f32 v[244:245], v[244:245], s[12:13], v[4:5] op_sel_hi:[1,0,1]
	v_pk_fma_f32 v[246:247], v[246:247], s[12:13], v[6:7] op_sel_hi:[1,0,1]
	v_pk_fma_f32 v[248:249], v[248:249], s[12:13], v[0:1] op_sel_hi:[1,0,1]
	v_pk_fma_f32 v[250:251], v[250:251], s[12:13], v[2:3] op_sel_hi:[1,0,1]
	s_add_u32 s82, s88, 0x58000
	s_addc_u32 s83, s89, 0
	v_cvt_pk_bf16_f32 v160, v236, v237
	v_cvt_pk_bf16_f32 v161, v238, v239
	global_store_dwordx2 v155, v[160:161], s[82:83]
	v_cvt_pk_bf16_f32 v162, v240, v241
	v_cvt_pk_bf16_f32 v163, v242, v243
	global_store_dwordx2 v155, v[162:163], s[82:83] offset:32
	v_cvt_pk_bf16_f32 v164, v244, v245
	v_cvt_pk_bf16_f32 v165, v246, v247
	global_store_dwordx2 v155, v[164:165], s[82:83] offset:256
	v_cvt_pk_bf16_f32 v166, v248, v249
	v_cvt_pk_bf16_f32 v167, v250, v251
	global_store_dwordx2 v155, v[166:167], s[82:83] offset:288
	v_add_f32_e32 v168, v236, v237
	v_add_f32_e32 v169, v238, v239
	v_mul_f32_e32 v172, v237, v237
	v_mul_f32_e32 v173, v239, v239
	v_add_f32_e32 v168, v168, v169
	v_fma_f32 v172, v236, v236, v172
	v_fma_f32 v173, v238, v238, v173
	v_add_f32_e32 v170, 0, v168
	v_add_f32_e32 v171, v172, v173
	v_add_f32_e32 v168, v240, v241
	v_add_f32_e32 v169, v242, v243
	v_mul_f32_e32 v172, v241, v241
	v_mul_f32_e32 v173, v243, v243
	v_add_f32_e32 v168, v168, v169
	v_fma_f32 v172, v240, v240, v172
	v_fma_f32 v173, v242, v242, v173
	v_add_f32_e32 v170, v170, v168
	v_add_f32_e32 v172, v172, v173
	v_add_f32_e32 v171, v171, v172
	v_add_f32_e32 v168, v244, v245
	v_add_f32_e32 v169, v246, v247
	v_mul_f32_e32 v172, v245, v245
	v_mul_f32_e32 v173, v247, v247
	v_add_f32_e32 v168, v168, v169
	v_fma_f32 v172, v244, v244, v172
	v_fma_f32 v173, v246, v246, v173
	v_add_f32_e32 v170, v170, v168
	v_add_f32_e32 v172, v172, v173
	v_add_f32_e32 v171, v171, v172
	v_add_f32_e32 v168, v248, v249
	v_add_f32_e32 v169, v250, v251
	v_mul_f32_e32 v172, v249, v249
	v_mul_f32_e32 v173, v251, v251
	v_add_f32_e32 v168, v168, v169
	v_fma_f32 v172, v248, v248, v172
	v_fma_f32 v173, v250, v250, v173
	v_add_f32_e32 v170, v170, v168
	v_add_f32_e32 v172, v172, v173
	v_add_f32_e32 v171, v171, v172
	ds_bpermute_b32 v174, v157, v170
	ds_bpermute_b32 v175, v157, v171
	s_waitcnt lgkmcnt(0)
	v_add_f32_e32 v170, v170, v174
	v_add_f32_e32 v171, v171, v175
	ds_bpermute_b32 v174, v158, v170
	ds_bpermute_b32 v175, v158, v171
	s_waitcnt lgkmcnt(0)
	v_add_f32_e32 v170, v170, v174
	v_add_f32_e32 v171, v171, v175
	s_and_saveexec_b64 s[22:23], s[2:3]
	global_atomic_add_f32 v156, v170, s[6:7] offset:1408
	global_atomic_add_f32 v156, v171, s[6:7] offset:1412
	s_or_b64 exec, exec, s[22:23]
	s_mov_b64 s[22:23], -1
